# phase 2: second workgroup of each CU walks its static item list in reverse so co-resident workgroups are in different item kinds
# speedup vs baseline: 1.0095x; 1.0017x over previous
.LBB0_388:
	s_andn2_b64 vcc, exec, s[4:5]
	s_cbranch_vccnz .LBB0_763
	v_readlane_b32 s4, v239, 9
	v_readlane_b32 s5, v239, 10
	s_andn2_b64 vcc, exec, s[4:5]
	s_cbranch_vccnz .LBB0_763
	s_lshl_b32 s4, s62, 10
	s_lshl_b32 s12, s62, 6
	s_ashr_i32 s5, s4, 31
	s_movk_i32 s41, 0x1fff
	s_movk_i32 s40, 0x2000
	s_movk_i32 s69, 0x1000
	v_writelane_b32 v239, s30, 48
	s_ashr_i32 s13, s12, 31
	s_lshl_b32 s46, s62, 9
	s_lshl_b32 s47, s62, 8
	s_lshl_b32 s63, s62, 3
	s_lshl_b64 s[14:15], s[4:5], 2
	s_mov_b32 s16, s66
	s_mov_b32 s100, s42
	s_getreg_b32 vcc_lo, hwreg(HW_REG_LDS_ALLOC, 0, 8)
	s_cmp_eq_u32 vcc_lo, 0
	s_cbranch_scc1 .Lp2_fwd
	s_sub_i32 s100, 0, s42
	s_add_i32 s16, s66, 0xc00
	s_cmp_lt_u32 s66, 64
	s_cbranch_scc0 .Lp2_fwd
	s_addk_i32 s16, 0x200
.Lp2_fwd:
	v_writelane_b32 v239, s31, 49
	s_branch .LBB0_394

.LBB0_393:
	s_add_i32 s16, s16, s100
	s_cmp_lt_i32 s16, 0
	s_cbranch_scc1 .LBB0_762
	s_cmpk_gt_i32 s16, 0xe3f
	s_cbranch_scc1 .LBB0_762
